# NA tile: only the rescale alpha exchange overlapped with the exp block (no PV read-ahead)
# baseline (speedup 1.0000x reference)
; __device__ __forceinline__ int crow(int r, int hi) { return (r & 3) + 8 * (r >> 2) + 4 * hi; }
; template <bool DIFF> ...
;     ...
;         const float mn = fmaxf(m1, mx), alpha = __builtin_amdgcn_exp2f((m1 - mn) * C), x1 = -mn * C; m1 = mn;
;         float ps = 0.f;
; #pragma unroll
;         for (int r = 0; r < 16; ++r) { a0[r] = __builtin_amdgcn_exp2f(fmaf(a0[r], C, x1)); ps += a0[r]; }
; #pragma unroll
;         for (int r = 0; r < 16; ++r) { a1[r] = __builtin_amdgcn_exp2f(fmaf(a1[r], C, x1)); ps += a1[r]; }
;         l1 = l1 * alpha + ps;
;         if (__any(alpha < 1.0f)) {
;           if (hi == 0) wsc[r32] = alpha;
;           asm volatile("s_waitcnt lgkmcnt(0)" ::: "memory");
; #pragma unroll
;           for (int r = 0; r < 16; ++r) { const float al = wsc[crow(r, hi)];
; #pragma unroll
;             for (int d = 0; d < 4; ++d) o[d][r] *= al; }
;         }
;         PK4(a0, 0, pa0); PK4(a0, 8, pa1); PK4(a1, 0, pa2); PK4(a1, 8, pa3);
.LBB0_438:
	v_mul_f32_e32 v81, 0xbe0293ee, v68
	v_fmamk_f32 v83, v185, 0x3e0293ee, v81
	v_exp_f32_e32 v83, v83
	v_fmamk_f32 v84, v153, 0x3e0293ee, v81
	v_exp_f32_e32 v84, v84
	v_fmamk_f32 v85, v99, 0x3e0293ee, v81
	v_exp_f32_e32 v85, v85
	v_fmamk_f32 v86, v98, 0x3e0293ee, v81
	v_exp_f32_e32 v86, v86
	v_fmamk_f32 v88, v101, 0x3e0293ee, v81
	v_add_f32_e32 v87, 0, v83
	v_exp_f32_e32 v88, v88
	v_fmamk_f32 v89, v100, 0x3e0293ee, v81
	v_add_f32_e32 v87, v84, v87
	v_exp_f32_e32 v89, v89
	v_fmamk_f32 v90, v103, 0x3e0293ee, v81
	v_add_f32_e32 v87, v85, v87
	v_exp_f32_e32 v90, v90
	v_fmamk_f32 v91, v102, 0x3e0293ee, v81
	v_add_f32_e32 v87, v86, v87
	v_exp_f32_e32 v91, v91
	v_fmamk_f32 v92, v105, 0x3e0293ee, v81
	v_add_f32_e32 v87, v88, v87
	v_exp_f32_e32 v92, v92
	v_fmamk_f32 v93, v104, 0x3e0293ee, v81
	v_add_f32_e32 v87, v89, v87
	v_exp_f32_e32 v93, v93
	v_fmamk_f32 v94, v107, 0x3e0293ee, v81
	v_add_f32_e32 v87, v90, v87
	v_exp_f32_e32 v94, v94
	v_fmamk_f32 v95, v106, 0x3e0293ee, v81
	v_add_f32_e32 v87, v91, v87
	v_exp_f32_e32 v95, v95
	v_fmamk_f32 v96, v109, 0x3e0293ee, v81
	v_add_f32_e32 v87, v92, v87
	v_exp_f32_e32 v96, v96
	v_fmamk_f32 v97, v108, 0x3e0293ee, v81
	v_add_f32_e32 v87, v93, v87
	v_exp_f32_e32 v97, v97
	v_fmamk_f32 v98, v111, 0x3e0293ee, v81
	v_add_f32_e32 v87, v94, v87
	v_exp_f32_e32 v98, v98
	v_fmamk_f32 v99, v110, 0x3e0293ee, v81
	v_add_f32_e32 v87, v95, v87
	v_exp_f32_e32 v99, v99
	v_fmamk_f32 v100, v113, 0x3e0293ee, v81
	v_add_f32_e32 v87, v96, v87
	v_exp_f32_e32 v100, v100
	v_fmamk_f32 v101, v112, 0x3e0293ee, v81
	v_add_f32_e32 v87, v97, v87
	v_exp_f32_e32 v101, v101
	v_fmamk_f32 v67, v67, 0x3e0293ee, v81
	v_add_f32_e32 v87, v98, v87
	v_exp_f32_e32 v67, v67
	v_fmamk_f32 v66, v66, 0x3e0293ee, v81
	v_add_f32_e32 v87, v99, v87
	v_exp_f32_e32 v66, v66
	v_fmamk_f32 v82, v82, 0x3e0293ee, v81
	v_add_f32_e32 v87, v100, v87
	v_exp_f32_e32 v82, v82
	v_fmamk_f32 v69, v69, 0x3e0293ee, v81
	v_add_f32_e32 v87, v101, v87
	v_exp_f32_e32 v69, v69
	v_fmamk_f32 v71, v71, 0x3e0293ee, v81
	v_add_f32_e32 v87, v67, v87
	v_exp_f32_e32 v102, v71
	v_fmamk_f32 v70, v70, 0x3e0293ee, v81
	v_add_f32_e32 v87, v66, v87
	v_exp_f32_e32 v103, v70
	v_fmamk_f32 v71, v73, 0x3e0293ee, v81
	v_add_f32_e32 v70, v82, v87
	v_exp_f32_e32 v87, v71
	v_fmamk_f32 v71, v72, 0x3e0293ee, v81
	v_add_f32_e32 v70, v69, v70
	v_exp_f32_e32 v104, v71
	v_fmamk_f32 v71, v75, 0x3e0293ee, v81
	v_add_f32_e32 v70, v102, v70
	v_exp_f32_e32 v105, v71
	v_fmamk_f32 v71, v74, 0x3e0293ee, v81
	v_add_f32_e32 v70, v103, v70
	v_exp_f32_e32 v106, v71
	v_fmamk_f32 v71, v77, 0x3e0293ee, v81
	v_add_f32_e32 v70, v87, v70
	v_exp_f32_e32 v107, v71
	v_fmamk_f32 v71, v76, 0x3e0293ee, v81
	v_add_f32_e32 v70, v104, v70
	v_exp_f32_e32 v108, v71
	v_fmamk_f32 v71, v79, 0x3e0293ee, v81
	v_add_f32_e32 v70, v105, v70
	v_exp_f32_e32 v109, v71
	v_fmac_f32_e32 v81, 0x3e0293ee, v78
	v_add_f32_e32 v70, v106, v70
	v_exp_f32_e32 v110, v81
	v_add_f32_e32 v70, v107, v70
	v_add_f32_e32 v70, v108, v70
	v_add_f32_e32 v70, v109, v70
	v_add_f32_e32 v111, v110, v70
	v_fmac_f32_e32 v111, v183, v80
	v_cvt_pk_bf16_f32 v70, v83, v84
	v_cvt_pk_bf16_f32 v71, v85, v86
	v_cvt_pk_bf16_f32 v72, v88, v89
	v_cvt_pk_bf16_f32 v73, v90, v91
	v_cvt_pk_bf16_f32 v74, v92, v93
	v_cvt_pk_bf16_f32 v75, v94, v95
	v_cvt_pk_bf16_f32 v76, v96, v97
	v_cvt_pk_bf16_f32 v77, v98, v99
	v_cvt_pk_bf16_f32 v78, v100, v101
	v_cvt_pk_bf16_f32 v79, v67, v66
	v_cvt_pk_bf16_f32 v80, v82, v69
	v_cvt_pk_bf16_f32 v81, v102, v103
	v_cvt_pk_bf16_f32 v82, v87, v104
	v_cvt_pk_bf16_f32 v83, v105, v106
	v_cvt_pk_bf16_f32 v84, v107, v108
	v_cvt_pk_bf16_f32 v85, v109, v110
	v_permlane32_swap_b32_e32 v70, v72
	v_permlane32_swap_b32_e32 v71, v73
	v_permlane32_swap_b32_e32 v74, v76
	v_permlane32_swap_b32_e32 v75, v77
	v_permlane32_swap_b32_e32 v78, v80
	v_permlane32_swap_b32_e32 v79, v81
	v_permlane32_swap_b32_e32 v82, v84
	v_permlane32_swap_b32_e32 v83, v85
	s_cmp_eq_u32 s32, 0
	s_cbranch_scc1 .Lna_rs_done
	s_waitcnt lgkmcnt(0)
	v_pk_mul_f32 v[62:63], v[62:63], v[118:119]
	v_pk_mul_f32 v[58:59], v[58:59], v[122:123]
	v_pk_mul_f32 v[54:55], v[54:55], v[126:127]
	v_pk_mul_f32 v[64:65], v[64:65], v[120:121]
	v_pk_mul_f32 v[60:61], v[60:61], v[124:125]
	v_pk_mul_f32 v[56:57], v[56:57], v[128:129]
	v_pk_mul_f32 v[52:53], v[52:53], v[116:117]
	v_pk_mul_f32 v[50:51], v[50:51], v[114:115]
	v_pk_mul_f32 v[46:47], v[46:47], v[118:119]
	v_pk_mul_f32 v[42:43], v[42:43], v[122:123]
	v_pk_mul_f32 v[38:39], v[38:39], v[126:127]
	v_pk_mul_f32 v[48:49], v[48:49], v[120:121]
	v_pk_mul_f32 v[44:45], v[44:45], v[124:125]
	v_pk_mul_f32 v[40:41], v[40:41], v[128:129]
	v_pk_mul_f32 v[36:37], v[36:37], v[116:117]
	v_pk_mul_f32 v[34:35], v[34:35], v[114:115]
	v_pk_mul_f32 v[30:31], v[30:31], v[118:119]
	v_pk_mul_f32 v[26:27], v[26:27], v[122:123]
	v_pk_mul_f32 v[22:23], v[22:23], v[126:127]
	v_pk_mul_f32 v[32:33], v[32:33], v[120:121]
	v_pk_mul_f32 v[28:29], v[28:29], v[124:125]
	v_pk_mul_f32 v[24:25], v[24:25], v[128:129]
	v_pk_mul_f32 v[20:21], v[20:21], v[116:117]
	v_pk_mul_f32 v[18:19], v[18:19], v[114:115]
	v_pk_mul_f32 v[14:15], v[14:15], v[118:119]
	v_pk_mul_f32 v[10:11], v[10:11], v[122:123]
	v_pk_mul_f32 v[6:7], v[6:7], v[126:127]
	v_pk_mul_f32 v[16:17], v[16:17], v[120:121]
	v_pk_mul_f32 v[12:13], v[12:13], v[124:125]
	v_pk_mul_f32 v[8:9], v[8:9], v[128:129]
	v_pk_mul_f32 v[4:5], v[4:5], v[116:117]
	v_pk_mul_f32 v[2:3], v[2:3], v[114:115]
; #define SBAR() __builtin_amdgcn_sched_barrier(0)
; template <int KS> __device__ __forceinline__ void pv_step(f32x16* o, int vb, bf16x8 pa) {
;   const s16x4 l0 = tr_read<v_rd_off(0, KS, 0)>(vb), h0 = tr_read<v_rd_off(0, KS, 1)>(vb), l1 = tr_read<v_rd_off(1, KS, 0)>(vb), h1 = tr_read<v_rd_off(1, KS, 1)>(vb);
;   const s16x4 l2 = tr_read<v_rd_off(2, KS, 0)>(vb), h2 = tr_read<v_rd_off(2, KS, 1)>(vb), l3 = tr_read<v_rd_off(3, KS, 0)>(vb), h3 = tr_read<v_rd_off(3, KS, 1)>(vb);
;   asm volatile("s_waitcnt lgkmcnt(0)" ::: "memory"); SBAR();
;     ...
;   o[0] = __builtin_amdgcn_mfma_f32_32x32x16_bf16(pa, PK(l0, h0), o[0], 0, 0, 0);
;   o[1] = __builtin_amdgcn_mfma_f32_32x32x16_bf16(pa, PK(l1, h1), o[1], 0, 0, 0);
;   o[2] = __builtin_amdgcn_mfma_f32_32x32x16_bf16(pa, PK(l2, h2), o[2], 0, 0, 0);
;   o[3] = __builtin_amdgcn_mfma_f32_32x32x16_bf16(pa, PK(l3, h3), o[3], 0, 0, 0);
;     ...
; }
; template <bool DIFF> ...
;     ...
;         PK4(a0, 0, pa0); PK4(a0, 8, pa1); PK4(a1, 0, pa2); PK4(a1, 8, pa3);
;         SBAR();
;         pv_step<0>(o, vb0, pa0); pv_step<1>(o, vb0, pa1); pv_step<2>(o, vb0, pa2); pv_step<3>(o, vb0, pa3);
.Lna_rs_done:
	ds_read_b64_tr_b16 v[86:87], v158 offset:0
	ds_read_b64_tr_b16 v[88:89], v158 offset:0x800
	ds_read_b64_tr_b16 v[90:91], v158 offset:0x200
	ds_read_b64_tr_b16 v[92:93], v158 offset:0xa00
	ds_read_b64_tr_b16 v[94:95], v158 offset:0x400
	ds_read_b64_tr_b16 v[96:97], v158 offset:0xc00
	ds_read_b64_tr_b16 v[98:99], v158 offset:0x600
	ds_read_b64_tr_b16 v[100:101], v158 offset:0xe00
	s_waitcnt lgkmcnt(0)
	s_nop 0
	v_mfma_f32_32x32x16_bf16 v[50:65], v[70:73], v[86:89], v[50:65]
	v_mfma_f32_32x32x16_bf16 v[34:49], v[70:73], v[90:93], v[34:49]
	v_mfma_f32_32x32x16_bf16 v[18:33], v[70:73], v[94:97], v[18:33]
	v_mfma_f32_32x32x16_bf16 v[2:17], v[70:73], v[98:101], v[2:17]
	ds_read_b64_tr_b16 v[70:71], v158 offset:0x1000
	ds_read_b64_tr_b16 v[72:73], v158 offset:0x1800
	ds_read_b64_tr_b16 v[86:87], v158 offset:0x1200
	ds_read_b64_tr_b16 v[88:89], v158 offset:0x1a00
	ds_read_b64_tr_b16 v[90:91], v158 offset:0x1400
	ds_read_b64_tr_b16 v[92:93], v158 offset:0x1c00
	ds_read_b64_tr_b16 v[94:95], v158 offset:0x1600
	ds_read_b64_tr_b16 v[96:97], v158 offset:0x1e00
	s_waitcnt lgkmcnt(0)
	s_nop 0
	v_mfma_f32_32x32x16_bf16 v[50:65], v[74:77], v[70:73], v[50:65]
	ds_read_b64_tr_b16 v[70:71], v158 offset:0x2000
	ds_read_b64_tr_b16 v[72:73], v158 offset:0x2800
	v_mfma_f32_32x32x16_bf16 v[34:49], v[74:77], v[86:89], v[34:49]
	v_mfma_f32_32x32x16_bf16 v[18:33], v[74:77], v[90:93], v[18:33]
	v_mfma_f32_32x32x16_bf16 v[2:17], v[74:77], v[94:97], v[2:17]
	ds_read_b64_tr_b16 v[74:75], v158 offset:0x2200
	ds_read_b64_tr_b16 v[76:77], v158 offset:0x2a00
	ds_read_b64_tr_b16 v[86:87], v158 offset:0x2400
	ds_read_b64_tr_b16 v[88:89], v158 offset:0x2c00
	ds_read_b64_tr_b16 v[90:91], v158 offset:0x2600
	ds_read_b64_tr_b16 v[92:93], v158 offset:0x2e00
	s_waitcnt lgkmcnt(0)
	v_mfma_f32_32x32x16_bf16 v[50:65], v[78:81], v[70:73], v[50:65]
	ds_read_b64_tr_b16 v[70:71], v158 offset:0x3000
	ds_read_b64_tr_b16 v[72:73], v158 offset:0x3800
	v_mfma_f32_32x32x16_bf16 v[34:49], v[78:81], v[74:77], v[34:49]
	ds_read_b64_tr_b16 v[74:75], v158 offset:0x3200
	ds_read_b64_tr_b16 v[76:77], v158 offset:0x3a00
	v_mfma_f32_32x32x16_bf16 v[18:33], v[78:81], v[86:89], v[18:33]
	v_mfma_f32_32x32x16_bf16 v[2:17], v[78:81], v[90:93], v[2:17]
	ds_read_b64_tr_b16 v[78:79], v158 offset:0x3400
	ds_read_b64_tr_b16 v[80:81], v158 offset:0x3c00
	ds_read_b64_tr_b16 v[86:87], v158 offset:0x3600
	ds_read_b64_tr_b16 v[88:89], v158 offset:0x3e00
	s_waitcnt lgkmcnt(0)
	v_mfma_f32_32x32x16_bf16 v[50:65], v[82:85], v[70:73], v[50:65]
	v_mov_b32_e32 v184, v68
	v_mov_b32_e32 v183, v111
	v_mfma_f32_32x32x16_bf16 v[34:49], v[82:85], v[74:77], v[34:49]
	v_mfma_f32_32x32x16_bf16 v[18:33], v[82:85], v[78:81], v[18:33]
	v_mfma_f32_32x32x16_bf16 v[2:17], v[82:85], v[86:89], v[2:17]
